# ret_u decay factors computed once per wave and kept in LDS; NA decode run once per item with scalars stashed in VGPR lanes
# baseline (speedup 1.0000x reference)
.LBB0_467:
	s_or_b64 exec, exec, s[2:3]
	v_mov_b32_e32 v2, v195
	v_mov_b32_e32 v1, v195
	s_barrier
	v_readlane_b32 s0, v253, 5
	v_ashrrev_i32_e32 v0, 6, v1
	s_movk_i32 s2, 0xa00
	v_lshl_add_u32 v122, s0, 3, v0
	v_cmp_gt_i32_e32 vcc, s2, v122
	s_and_saveexec_b64 s[2:3], vcc
	s_xor_b64 s[2:3], exec, s[2:3]
	s_cbranch_execz .LBB0_475
	v_and_b32_e32 v123, 15, v2
	v_bfe_u32 v1, v1, 6, 2
	v_lshl_or_b32 v125, v1, 6, v123
	v_bfe_u32 v2, v2, 4, 2
	v_lshl_or_b32 v192, s36, 3, v1
	v_mul_u32_u24_e32 v1, 0x14000, v125
	v_lshlrev_b32_e32 v3, 3, v2
	v_lshl_add_u64 v[88:89], v[192:193], 2, s[48:49]
	v_lshlrev_b32_e32 v192, 4, v2
	v_lshlrev_b32_e32 v1, 1, v1
	v_readlane_b32 s4, v253, 1
	v_lshlrev_b32_e32 v124, 8, v2
	v_or_b32_e32 v141, 7, v3
	v_xor_b32_e32 v142, 0x78, v3
	v_or_b32_e32 v2, v1, v192
	v_mov_b32_e32 v3, v193
	v_readlane_b32 s5, v253, 2
	v_lshlrev_b32_e32 v0, 5, v0
	v_or_b32_e32 v126, 0xc00, v124
	v_or_b32_e32 v127, 64, v124
	v_or_b32_e32 v128, 0x80, v124
	v_or_b32_e32 v129, 0xc0, v124
	v_or_b32_e32 v130, 0x400, v124
	v_or_b32_e32 v131, 0x440, v124
	v_or_b32_e32 v132, 0x480, v124
	v_or_b32_e32 v133, 0x4c0, v124
	v_or_b32_e32 v134, 0x800, v124
	v_or_b32_e32 v135, 0x840, v124
	v_or_b32_e32 v136, 0x880, v124
	v_or_b32_e32 v137, 0x8c0, v124
	v_or_b32_e32 v138, 0xc40, v124
	v_or_b32_e32 v139, 0xc80, v124
	v_or_b32_e32 v140, 0xcc0, v124
	v_lshl_add_u64 v[90:91], s[4:5], 0, v[2:3]
	v_lshl_add_u32 v143, s0, 8, v0
	v_lshl_add_u64 v[92:93], s[4:5], 0, v[192:193]
	s_mov_b64 s[4:5], 0
	v_lshrrev_b32_e32 v154, 6, v195
	v_lshlrev_b32_e32 v154, 10, v154
	v_bfe_u32 v155, v195, 4, 2
	v_lshl_or_b32 v154, v155, 6, v154
	s_mov_b32 s101, 0

.LBB0_470:
	v_or_b32_e32 v0, s0, v125
	v_mul_u32_u24_e32 v192, 0x14000, v0
	v_mov_b32_e32 v0, 0
	s_xor_b64 s[6:7], s[8:9], -1
	v_lshl_add_u64 v[102:103], v[192:193], 1, v[100:101]
	s_mov_b64 s[8:9], 0
	v_mov_b32_e32 v146, v142
	v_mov_b32_e32 v147, v141
	v_mov_b32_e32 v155, v154
	v_mov_b32_e32 v1, v0
	v_mov_b32_e32 v2, v0
	v_mov_b32_e32 v3, v0
	v_mov_b32_e32 v8, v0
	v_mov_b32_e32 v9, v0
	v_mov_b32_e32 v10, v0
	v_mov_b32_e32 v11, v0
	v_mov_b32_e32 v16, v0
	v_mov_b32_e32 v17, v0
	v_mov_b32_e32 v18, v0
	v_mov_b32_e32 v19, v0
	v_mov_b32_e32 v24, v0
	v_mov_b32_e32 v25, v0
	v_mov_b32_e32 v26, v0
	v_mov_b32_e32 v27, v0
	v_mov_b32_e32 v32, v0
	v_mov_b32_e32 v33, v0
	v_mov_b32_e32 v34, v0
	v_mov_b32_e32 v35, v0
	v_mov_b32_e32 v40, v0
	v_mov_b32_e32 v41, v0
	v_mov_b32_e32 v42, v0
	v_mov_b32_e32 v43, v0
	v_mov_b32_e32 v48, v0
	v_mov_b32_e32 v49, v0
	v_mov_b32_e32 v50, v0
	v_mov_b32_e32 v51, v0
	v_mov_b32_e32 v52, v0
	v_mov_b32_e32 v53, v0
	v_mov_b32_e32 v54, v0
	v_mov_b32_e32 v55, v0
	v_mov_b32_e32 v4, v0
	v_mov_b32_e32 v5, v0
	v_mov_b32_e32 v6, v0
	v_mov_b32_e32 v7, v0
	v_mov_b32_e32 v12, v0
	v_mov_b32_e32 v13, v0
	v_mov_b32_e32 v14, v0
	v_mov_b32_e32 v15, v0
	v_mov_b32_e32 v20, v0
	v_mov_b32_e32 v21, v0
	v_mov_b32_e32 v22, v0
	v_mov_b32_e32 v23, v0
	v_mov_b32_e32 v28, v0
	v_mov_b32_e32 v29, v0
	v_mov_b32_e32 v30, v0
	v_mov_b32_e32 v31, v0
	v_mov_b32_e32 v36, v0
	v_mov_b32_e32 v37, v0
	v_mov_b32_e32 v38, v0
	v_mov_b32_e32 v39, v0
	v_mov_b32_e32 v44, v0
	v_mov_b32_e32 v45, v0
	v_mov_b32_e32 v46, v0
	v_mov_b32_e32 v47, v0
	v_mov_b32_e32 v56, v0
	v_mov_b32_e32 v57, v0
	v_mov_b32_e32 v58, v0
	v_mov_b32_e32 v59, v0
	v_mov_b32_e32 v60, v0
	v_mov_b32_e32 v61, v0
	v_mov_b32_e32 v62, v0
	v_mov_b32_e32 v63, v0
.LBB0_471:
	s_cmp_lg_u32 s101, 0
	s_cbranch_scc1 .Lru_rd
	v_add_u32_e32 v152, 7, v146
	v_cvt_f32_u32_e32 v152, v152
	v_mul_f32_e32 v153, v144, v152
	v_cmp_gt_f32_e32 vcc, s96, v153
	s_nop 1
	v_cndmask_b32_e32 v153, 0, v225, vcc
	v_fmac_f32_e32 v153, v144, v152
	v_exp_f32_e32 v152, v153
	v_cndmask_b32_e32 v153, 0, v226, vcc
	v_ldexp_f32 v104, v152, v153
	v_add_u32_e32 v152, 6, v146
	v_cvt_f32_u32_e32 v152, v152
	v_mul_f32_e32 v153, v144, v152
	v_cmp_gt_f32_e32 vcc, s96, v153
	s_nop 1
	v_cndmask_b32_e32 v153, 0, v225, vcc
	v_fmac_f32_e32 v153, v144, v152
	v_exp_f32_e32 v152, v153
	v_cndmask_b32_e32 v153, 0, v226, vcc
	v_ldexp_f32 v105, v152, v153
	v_add_u32_e32 v152, -7, v147
	v_cvt_f32_u32_e32 v152, v152
	v_mul_f32_e32 v153, v145, v152
	v_cmp_gt_f32_e32 vcc, s96, v153
	s_nop 1
	v_cndmask_b32_e32 v153, 0, v225, vcc
	v_fmac_f32_e32 v153, v145, v152
	v_exp_f32_e32 v152, v153
	v_cndmask_b32_e32 v153, 0, v226, vcc
	v_ldexp_f32 v106, v152, v153
	v_add_u32_e32 v152, -6, v147
	v_cvt_f32_u32_e32 v152, v152
	v_mul_f32_e32 v153, v145, v152
	v_cmp_gt_f32_e32 vcc, s96, v153
	s_nop 1
	v_cndmask_b32_e32 v153, 0, v225, vcc
	v_fmac_f32_e32 v153, v145, v152
	v_exp_f32_e32 v152, v153
	v_cndmask_b32_e32 v153, 0, v226, vcc
	v_ldexp_f32 v107, v152, v153
	v_add_u32_e32 v152, 5, v146
	v_cvt_f32_u32_e32 v152, v152
	v_mul_f32_e32 v153, v144, v152
	v_cmp_gt_f32_e32 vcc, s96, v153
	s_nop 1
	v_cndmask_b32_e32 v153, 0, v225, vcc
	v_fmac_f32_e32 v153, v144, v152
	v_exp_f32_e32 v152, v153
	v_cndmask_b32_e32 v153, 0, v226, vcc
	v_ldexp_f32 v108, v152, v153
	v_add_u32_e32 v152, 4, v146
	v_cvt_f32_u32_e32 v152, v152
	v_mul_f32_e32 v153, v144, v152
	v_cmp_gt_f32_e32 vcc, s96, v153
	s_nop 1
	v_cndmask_b32_e32 v153, 0, v225, vcc
	v_fmac_f32_e32 v153, v144, v152
	v_exp_f32_e32 v152, v153
	v_cndmask_b32_e32 v153, 0, v226, vcc
	v_ldexp_f32 v109, v152, v153
	v_add_u32_e32 v152, -5, v147
	v_cvt_f32_u32_e32 v152, v152
	v_mul_f32_e32 v153, v145, v152
	v_cmp_gt_f32_e32 vcc, s96, v153
	s_nop 1
	v_cndmask_b32_e32 v153, 0, v225, vcc
	v_fmac_f32_e32 v153, v145, v152
	v_exp_f32_e32 v152, v153
	v_cndmask_b32_e32 v153, 0, v226, vcc
	v_ldexp_f32 v110, v152, v153
	v_add_u32_e32 v152, -4, v147
	v_cvt_f32_u32_e32 v152, v152
	v_mul_f32_e32 v153, v145, v152
	v_cmp_gt_f32_e32 vcc, s96, v153
	s_nop 1
	v_cndmask_b32_e32 v153, 0, v225, vcc
	v_fmac_f32_e32 v153, v145, v152
	v_exp_f32_e32 v152, v153
	v_cndmask_b32_e32 v153, 0, v226, vcc
	v_ldexp_f32 v111, v152, v153
	v_add_u32_e32 v152, 3, v146
	v_cvt_f32_u32_e32 v152, v152
	v_mul_f32_e32 v153, v144, v152
	v_cmp_gt_f32_e32 vcc, s96, v153
	s_nop 1
	v_cndmask_b32_e32 v153, 0, v225, vcc
	v_fmac_f32_e32 v153, v144, v152
	v_exp_f32_e32 v152, v153
	v_cndmask_b32_e32 v153, 0, v226, vcc
	v_ldexp_f32 v112, v152, v153
	v_add_u32_e32 v152, 2, v146
	v_cvt_f32_u32_e32 v152, v152
	v_mul_f32_e32 v153, v144, v152
	v_cmp_gt_f32_e32 vcc, s96, v153
	s_nop 1
	v_cndmask_b32_e32 v153, 0, v225, vcc
	v_fmac_f32_e32 v153, v144, v152
	v_exp_f32_e32 v152, v153
	v_cndmask_b32_e32 v153, 0, v226, vcc
	v_ldexp_f32 v113, v152, v153
	v_add_u32_e32 v152, -3, v147
	v_cvt_f32_u32_e32 v152, v152
	v_mul_f32_e32 v153, v145, v152
	v_cmp_gt_f32_e32 vcc, s96, v153
	s_nop 1
	v_cndmask_b32_e32 v153, 0, v225, vcc
	v_fmac_f32_e32 v153, v145, v152
	v_exp_f32_e32 v152, v153
	v_cndmask_b32_e32 v153, 0, v226, vcc
	v_ldexp_f32 v114, v152, v153
	v_add_u32_e32 v152, -2, v147
	v_cvt_f32_u32_e32 v152, v152
	v_mul_f32_e32 v153, v145, v152
	v_cmp_gt_f32_e32 vcc, s96, v153
	s_nop 1
	v_cndmask_b32_e32 v153, 0, v225, vcc
	v_fmac_f32_e32 v153, v145, v152
	v_exp_f32_e32 v152, v153
	v_cndmask_b32_e32 v153, 0, v226, vcc
	v_ldexp_f32 v115, v152, v153
	v_add_u32_e32 v152, 1, v146
	v_cvt_f32_u32_e32 v152, v152
	v_mul_f32_e32 v153, v144, v152
	v_cmp_gt_f32_e32 vcc, s96, v153
	s_nop 1
	v_cndmask_b32_e32 v153, 0, v225, vcc
	v_fmac_f32_e32 v153, v144, v152
	v_exp_f32_e32 v152, v153
	v_cndmask_b32_e32 v153, 0, v226, vcc
	v_ldexp_f32 v116, v152, v153
	v_cvt_f32_u32_e32 v152, v146
	v_mul_f32_e32 v153, v144, v152
	v_cmp_gt_f32_e32 vcc, s96, v153
	s_nop 1
	v_cndmask_b32_e32 v153, 0, v225, vcc
	v_fmac_f32_e32 v153, v144, v152
	v_exp_f32_e32 v152, v153
	v_cndmask_b32_e32 v153, 0, v226, vcc
	v_ldexp_f32 v117, v152, v153
	v_add_u32_e32 v152, -1, v147
	v_cvt_f32_u32_e32 v152, v152
	v_mul_f32_e32 v153, v145, v152
	v_cmp_gt_f32_e32 vcc, s96, v153
	s_nop 1
	v_cndmask_b32_e32 v153, 0, v225, vcc
	v_fmac_f32_e32 v153, v145, v152
	v_exp_f32_e32 v152, v153
	v_cndmask_b32_e32 v153, 0, v226, vcc
	v_ldexp_f32 v118, v152, v153
	v_cvt_f32_u32_e32 v152, v147
	v_mul_f32_e32 v153, v145, v152
	v_cmp_gt_f32_e32 vcc, s96, v153
	s_nop 1
	v_cndmask_b32_e32 v153, 0, v225, vcc
	v_fmac_f32_e32 v153, v145, v152
	v_exp_f32_e32 v152, v153
	v_cndmask_b32_e32 v153, 0, v226, vcc
	v_ldexp_f32 v119, v152, v153
	ds_write_b128 v155, v[104:107]
	ds_write_b128 v155, v[108:111] offset:16
	ds_write_b128 v155, v[112:115] offset:32
	ds_write_b128 v155, v[116:119] offset:48
	s_branch .Lru_dn
.Lru_rd:
	ds_read_b128 v[104:107], v155
	ds_read_b128 v[108:111], v155 offset:16
	ds_read_b128 v[112:115], v155 offset:32
	ds_read_b128 v[116:119], v155 offset:48
.Lru_dn:
	v_add_u32_e32 v155, 0x100, v155
	v_lshl_add_u64 v[76:77], v[94:95], 0, s[8:9]
	s_mov_b32 s10, 0x15ed8000
	v_add_co_u32_e32 v64, vcc, s10, v76
	s_mov_b32 s10, 0x16158000
	s_nop 0
	v_addc_co_u32_e32 v65, vcc, 0, v77, vcc
	v_add_co_u32_e32 v68, vcc, s10, v76
	s_mov_b32 s10, 0x163d8000
	s_nop 0
	v_addc_co_u32_e32 v69, vcc, 0, v77, vcc
	v_add_co_u32_e32 v72, vcc, s10, v76
	s_mov_b32 s10, 0x16658000
	s_nop 0
	v_addc_co_u32_e32 v73, vcc, 0, v77, vcc
	v_add_co_u32_e32 v76, vcc, s10, v76
	v_lshl_add_u64 v[120:121], v[102:103], 0, s[8:9]
	s_nop 0
	v_addc_co_u32_e32 v77, vcc, 0, v77, vcc
	s_mov_b32 s10, 0x136d8000
	v_add_co_u32_e32 v80, vcc, s10, v120
	s_nop 0
	v_addc_co_u32_e32 v81, vcc, 0, v121, vcc
	global_load_dwordx4 v[80:83], v[80:81], off
	global_load_dwordx4 v[64:67], v[64:65], off
	global_load_dwordx4 v[68:71], v[68:69], off
	s_mov_b32 s10, 0x13958000
	global_load_dwordx4 v[72:75], v[72:73], off
	s_add_u32 s8, s8, 64
	global_load_dwordx4 v[76:79], v[76:77], off
	s_addc_u32 s9, s9, 0
	s_cmpk_eq_i32 s8, 0x100
	s_waitcnt vmcnt(4)
	v_and_b32_e32 v149, 0xffff0000, v83
	v_lshlrev_b32_e32 v84, 16, v80
	v_and_b32_e32 v85, 0xffff0000, v80
	s_waitcnt lgkmcnt(0)
	v_pk_mul_f32 v[86:87], v[104:105], v[84:85]
	v_pk_mul_f32 v[84:85], v[106:107], v[84:85]
	v_cvt_pk_bf16_f32 v80, v86, v87
	v_cvt_pk_bf16_f32 v84, v84, v85
	v_and_b32_e32 v87, 0xffff0000, v81
	s_nop 0
	v_lshlrev_b32_e32 v86, 16, v81
	v_pk_mul_f32 v[156:157], v[108:109], v[86:87]
	v_pk_mul_f32 v[86:87], v[110:111], v[86:87]
	v_cvt_pk_bf16_f32 v81, v156, v157
	v_cvt_pk_bf16_f32 v85, v86, v87
	v_lshlrev_b32_e32 v86, 16, v82
	v_and_b32_e32 v87, 0xffff0000, v82
	v_pk_mul_f32 v[158:159], v[112:113], v[86:87]
	v_pk_mul_f32 v[86:87], v[114:115], v[86:87]
	v_cvt_pk_bf16_f32 v82, v158, v159
	v_cvt_pk_bf16_f32 v86, v86, v87
	v_subrev_u32_e32 v146, 32, v146
	v_add_u32_e32 v147, 32, v147
	v_lshlrev_b32_e32 v148, 16, v83
	v_pk_mul_f32 v[150:151], v[116:117], v[148:149]
	v_cvt_pk_bf16_f32 v83, v150, v151
	v_pk_mul_f32 v[148:149], v[118:119], v[148:149]
	s_waitcnt vmcnt(3)
	v_mfma_f32_16x16x32_bf16 v[52:55], v[64:67], v[80:83], v[52:55]
	v_cvt_pk_bf16_f32 v87, v148, v149
	s_waitcnt vmcnt(2)
	v_mfma_f32_16x16x32_bf16 v[40:43], v[68:71], v[80:83], v[40:43]
	s_waitcnt vmcnt(1)
	v_mfma_f32_16x16x32_bf16 v[24:27], v[72:75], v[80:83], v[24:27]
	s_waitcnt vmcnt(0)
	v_mfma_f32_16x16x32_bf16 v[8:11], v[76:79], v[80:83], v[8:11]
	v_add_co_u32_e32 v80, vcc, s10, v120
	s_nop 1
	v_addc_co_u32_e32 v81, vcc, 0, v121, vcc
	global_load_dwordx4 v[80:83], v[80:81], off
	v_mfma_f32_16x16x32_bf16 v[60:63], v[64:67], v[84:87], v[60:63]
	v_mfma_f32_16x16x32_bf16 v[44:47], v[68:71], v[84:87], v[44:47]
	v_mfma_f32_16x16x32_bf16 v[28:31], v[72:75], v[84:87], v[28:31]
	v_mfma_f32_16x16x32_bf16 v[12:15], v[76:79], v[84:87], v[12:15]
	s_waitcnt vmcnt(0)
	v_lshlrev_b32_e32 v84, 16, v80
	v_and_b32_e32 v85, 0xffff0000, v80
	v_pk_mul_f32 v[86:87], v[104:105], v[84:85]
	v_pk_mul_f32 v[84:85], v[106:107], v[84:85]
	v_cvt_pk_bf16_f32 v80, v86, v87
	v_lshlrev_b32_e32 v86, 16, v81
	v_and_b32_e32 v87, 0xffff0000, v81
	v_pk_mul_f32 v[104:105], v[108:109], v[86:87]
	v_pk_mul_f32 v[86:87], v[110:111], v[86:87]
	v_cvt_pk_bf16_f32 v84, v84, v85
	v_cvt_pk_bf16_f32 v85, v86, v87
	v_lshlrev_b32_e32 v86, 16, v82
	v_and_b32_e32 v87, 0xffff0000, v82
	v_cvt_pk_bf16_f32 v81, v104, v105
	v_pk_mul_f32 v[104:105], v[112:113], v[86:87]
	v_pk_mul_f32 v[86:87], v[114:115], v[86:87]
	v_cvt_pk_bf16_f32 v82, v104, v105
	v_lshlrev_b32_e32 v104, 16, v83
	v_and_b32_e32 v105, 0xffff0000, v83
	v_pk_mul_f32 v[106:107], v[116:117], v[104:105]
	v_pk_mul_f32 v[104:105], v[118:119], v[104:105]
	v_cvt_pk_bf16_f32 v86, v86, v87
	v_cvt_pk_bf16_f32 v83, v106, v107
	v_cvt_pk_bf16_f32 v87, v104, v105
	s_nop 0
	v_mfma_f32_16x16x32_bf16 v[48:51], v[64:67], v[80:83], v[48:51]
	v_mfma_f32_16x16x32_bf16 v[56:59], v[64:67], v[84:87], v[56:59]
	v_mfma_f32_16x16x32_bf16 v[32:35], v[68:71], v[80:83], v[32:35]
	v_mfma_f32_16x16x32_bf16 v[36:39], v[68:71], v[84:87], v[36:39]
	v_mfma_f32_16x16x32_bf16 v[16:19], v[72:75], v[80:83], v[16:19]
	v_mfma_f32_16x16x32_bf16 v[20:23], v[72:75], v[84:87], v[20:23]
	v_mfma_f32_16x16x32_bf16 v[0:3], v[76:79], v[80:83], v[0:3]
	v_mfma_f32_16x16x32_bf16 v[4:7], v[76:79], v[84:87], v[4:7]
	s_cbranch_scc0 .LBB0_471
	s_mov_b32 s101, 1
	v_or_b32_e32 v68, s0, v123
	v_or_b32_e32 v192, v68, v124
	v_lshlrev_b64 v[64:65], 2, v[192:193]
	v_lshl_add_u64 v[66:67], v[96:97], 0, v[64:65]
	v_lshl_add_u64 v[64:65], v[98:99], 0, v[64:65]
	v_add_u32_e32 v192, v68, v124
	global_store_dword v[64:65], v60, off
	v_lshlrev_b64 v[64:65], 2, v[192:193]
	global_store_dword v[66:67], v52, off
	v_lshl_add_u64 v[66:67], v[96:97], 0, v[64:65]
	global_store_dword v[66:67], v53, off offset:256
	v_lshl_add_u64 v[52:53], v[98:99], 0, v[64:65]
	v_add_u32_e32 v192, v68, v127
	global_store_dword v[52:53], v61, off offset:256
	global_store_dword v[66:67], v54, off offset:512
	global_store_dword v[52:53], v62, off offset:512
	global_store_dword v[66:67], v55, off offset:768
	global_store_dword v[52:53], v63, off offset:768
	global_store_dword v[66:67], v48, off offset:64
	global_store_dword v[52:53], v56, off offset:64
	v_lshlrev_b64 v[52:53], 2, v[192:193]
	v_lshl_add_u64 v[54:55], v[96:97], 0, v[52:53]
	global_store_dword v[54:55], v49, off offset:64
	v_lshl_add_u64 v[48:49], v[98:99], 0, v[52:53]
	v_add_u32_e32 v192, v68, v128
	global_store_dword v[48:49], v57, off offset:64
	v_lshlrev_b64 v[48:49], 2, v[192:193]
	v_lshl_add_u64 v[52:53], v[96:97], 0, v[48:49]
	v_lshl_add_u64 v[48:49], v[98:99], 0, v[48:49]
	v_add_u32_e32 v192, v68, v129
	global_store_dword v[48:49], v58, off offset:64
	v_lshlrev_b64 v[48:49], 2, v[192:193]
	global_store_dword v[52:53], v50, off offset:64
	v_lshl_add_u64 v[52:53], v[96:97], 0, v[48:49]
	v_lshl_add_u64 v[48:49], v[98:99], 0, v[48:49]
	v_or_b32_e32 v192, v68, v130
	global_store_dword v[48:49], v59, off offset:64
	v_lshlrev_b64 v[48:49], 2, v[192:193]
	global_store_dword v[52:53], v51, off offset:64
	v_lshl_add_u64 v[50:51], v[96:97], 0, v[48:49]
	v_lshl_add_u64 v[48:49], v[98:99], 0, v[48:49]
	v_or_b32_e32 v192, v68, v131
	global_store_dword v[48:49], v44, off
	v_lshlrev_b64 v[48:49], 2, v[192:193]
	global_store_dword v[50:51], v40, off
	v_lshl_add_u64 v[50:51], v[96:97], 0, v[48:49]
	global_store_dword v[50:51], v41, off
	v_lshl_add_u64 v[40:41], v[98:99], 0, v[48:49]
	v_or_b32_e32 v192, v68, v132
	global_store_dword v[40:41], v45, off
	v_lshlrev_b64 v[40:41], 2, v[192:193]
	v_lshl_add_u64 v[44:45], v[96:97], 0, v[40:41]
	v_lshl_add_u64 v[40:41], v[98:99], 0, v[40:41]
	v_or_b32_e32 v192, v68, v133
	global_store_dword v[40:41], v46, off
	v_lshlrev_b64 v[40:41], 2, v[192:193]
	global_store_dword v[44:45], v42, off
	v_lshl_add_u64 v[44:45], v[96:97], 0, v[40:41]
	v_lshl_add_u64 v[40:41], v[98:99], 0, v[40:41]
	v_add_u32_e32 v192, v68, v130
	global_store_dword v[40:41], v47, off
	v_lshlrev_b64 v[40:41], 2, v[192:193]
	global_store_dword v[44:45], v43, off
	v_lshl_add_u64 v[42:43], v[96:97], 0, v[40:41]
	v_lshl_add_u64 v[40:41], v[98:99], 0, v[40:41]
	v_add_u32_e32 v192, v68, v131
	global_store_dword v[40:41], v36, off offset:64
	v_lshlrev_b64 v[40:41], 2, v[192:193]
	global_store_dword v[42:43], v32, off offset:64
	v_lshl_add_u64 v[42:43], v[96:97], 0, v[40:41]
	global_store_dword v[42:43], v33, off offset:64
	v_lshl_add_u64 v[32:33], v[98:99], 0, v[40:41]
	v_add_u32_e32 v192, v68, v132
	global_store_dword v[32:33], v37, off offset:64
	v_lshlrev_b64 v[32:33], 2, v[192:193]
	v_lshl_add_u64 v[36:37], v[96:97], 0, v[32:33]
	v_lshl_add_u64 v[32:33], v[98:99], 0, v[32:33]
	v_add_u32_e32 v192, v68, v133
	global_store_dword v[32:33], v38, off offset:64
	v_lshlrev_b64 v[32:33], 2, v[192:193]
	global_store_dword v[36:37], v34, off offset:64
	v_lshl_add_u64 v[36:37], v[96:97], 0, v[32:33]
	v_lshl_add_u64 v[32:33], v[98:99], 0, v[32:33]
	v_or_b32_e32 v192, v68, v134
	global_store_dword v[32:33], v39, off offset:64
	v_lshlrev_b64 v[32:33], 2, v[192:193]
	global_store_dword v[36:37], v35, off offset:64
	v_lshl_add_u64 v[34:35], v[96:97], 0, v[32:33]
	v_lshl_add_u64 v[32:33], v[98:99], 0, v[32:33]
	v_or_b32_e32 v192, v68, v135
	global_store_dword v[32:33], v28, off
	v_lshlrev_b64 v[32:33], 2, v[192:193]
	global_store_dword v[34:35], v24, off
	v_lshl_add_u64 v[34:35], v[96:97], 0, v[32:33]
	global_store_dword v[34:35], v25, off
	v_lshl_add_u64 v[24:25], v[98:99], 0, v[32:33]
	v_or_b32_e32 v192, v68, v136
	global_store_dword v[24:25], v29, off
	v_lshlrev_b64 v[24:25], 2, v[192:193]
	v_lshl_add_u64 v[28:29], v[96:97], 0, v[24:25]
	v_lshl_add_u64 v[24:25], v[98:99], 0, v[24:25]
	v_or_b32_e32 v192, v68, v137
	global_store_dword v[24:25], v30, off
	v_lshlrev_b64 v[24:25], 2, v[192:193]
	global_store_dword v[28:29], v26, off
	v_lshl_add_u64 v[28:29], v[96:97], 0, v[24:25]
	v_lshl_add_u64 v[24:25], v[98:99], 0, v[24:25]
	v_add_u32_e32 v192, v68, v134
	global_store_dword v[24:25], v31, off
	v_lshlrev_b64 v[24:25], 2, v[192:193]
	global_store_dword v[28:29], v27, off
	v_lshl_add_u64 v[26:27], v[96:97], 0, v[24:25]
	v_lshl_add_u64 v[24:25], v[98:99], 0, v[24:25]
	v_add_u32_e32 v192, v68, v135
	global_store_dword v[24:25], v20, off offset:64
	v_lshlrev_b64 v[24:25], 2, v[192:193]
	global_store_dword v[26:27], v16, off offset:64
	v_lshl_add_u64 v[26:27], v[96:97], 0, v[24:25]
	global_store_dword v[26:27], v17, off offset:64
	v_lshl_add_u64 v[16:17], v[98:99], 0, v[24:25]
	v_add_u32_e32 v192, v68, v136
	global_store_dword v[16:17], v21, off offset:64
	v_lshlrev_b64 v[16:17], 2, v[192:193]
	v_lshl_add_u64 v[20:21], v[96:97], 0, v[16:17]
	v_lshl_add_u64 v[16:17], v[98:99], 0, v[16:17]
	v_add_u32_e32 v192, v68, v137
	global_store_dword v[16:17], v22, off offset:64
	v_lshlrev_b64 v[16:17], 2, v[192:193]
	global_store_dword v[20:21], v18, off offset:64
	v_lshl_add_u64 v[20:21], v[96:97], 0, v[16:17]
	v_lshl_add_u64 v[16:17], v[98:99], 0, v[16:17]
	v_or_b32_e32 v192, v68, v126
	global_store_dword v[16:17], v23, off offset:64
	v_lshlrev_b64 v[16:17], 2, v[192:193]
	global_store_dword v[20:21], v19, off offset:64
	v_lshl_add_u64 v[18:19], v[96:97], 0, v[16:17]
	v_lshl_add_u64 v[16:17], v[98:99], 0, v[16:17]
	v_or_b32_e32 v192, v68, v138
	global_store_dword v[16:17], v12, off
	v_lshlrev_b64 v[16:17], 2, v[192:193]
	global_store_dword v[18:19], v8, off
	v_lshl_add_u64 v[18:19], v[96:97], 0, v[16:17]
	global_store_dword v[18:19], v9, off
	v_lshl_add_u64 v[8:9], v[98:99], 0, v[16:17]
	v_or_b32_e32 v192, v68, v139
	global_store_dword v[8:9], v13, off
	v_lshlrev_b64 v[8:9], 2, v[192:193]
	v_lshl_add_u64 v[12:13], v[96:97], 0, v[8:9]
	v_lshl_add_u64 v[8:9], v[98:99], 0, v[8:9]
	v_or_b32_e32 v192, v68, v140
	global_store_dword v[8:9], v14, off
	v_lshlrev_b64 v[8:9], 2, v[192:193]
	global_store_dword v[12:13], v10, off
	v_lshl_add_u64 v[12:13], v[96:97], 0, v[8:9]
	v_lshl_add_u64 v[8:9], v[98:99], 0, v[8:9]
	v_add_u32_e32 v192, v68, v126
	global_store_dword v[8:9], v15, off
	v_lshlrev_b64 v[8:9], 2, v[192:193]
	global_store_dword v[12:13], v11, off
	v_lshl_add_u64 v[10:11], v[96:97], 0, v[8:9]
	v_lshl_add_u64 v[8:9], v[98:99], 0, v[8:9]
	v_add_u32_e32 v192, v68, v138
	global_store_dword v[8:9], v4, off offset:64
	v_lshlrev_b64 v[8:9], 2, v[192:193]
	global_store_dword v[10:11], v0, off offset:64
	v_lshl_add_u64 v[10:11], v[96:97], 0, v[8:9]
	global_store_dword v[10:11], v1, off offset:64
	v_lshl_add_u64 v[0:1], v[98:99], 0, v[8:9]
	v_add_u32_e32 v192, v68, v139
	global_store_dword v[0:1], v5, off offset:64
	v_lshlrev_b64 v[0:1], 2, v[192:193]
	v_lshl_add_u64 v[4:5], v[96:97], 0, v[0:1]
	v_lshl_add_u64 v[0:1], v[98:99], 0, v[0:1]
	v_add_u32_e32 v192, v68, v140
	global_store_dword v[0:1], v6, off offset:64
	v_lshlrev_b64 v[0:1], 2, v[192:193]
	global_store_dword v[4:5], v2, off offset:64
	v_lshl_add_u64 v[4:5], v[96:97], 0, v[0:1]
	v_lshl_add_u64 v[0:1], v[98:99], 0, v[0:1]
	s_mov_b32 s0, 32
	s_mov_b64 s[8:9], 0
	s_and_b64 vcc, exec, s[6:7]
	global_store_dword v[4:5], v3, off offset:64
	global_store_dword v[0:1], v7, off offset:64
	s_cbranch_vccz .LBB0_470
	v_readlane_b32 s0, v253, 50
	s_nop 1
	v_add_u32_e32 v122, s0, v122
	v_cmp_lt_i32_e32 vcc, s78, v122
	v_readlane_b32 s0, v254, 31
	s_or_b64 s[4:5], vcc, s[4:5]
	s_nop 0
	v_add_u32_e32 v143, s0, v143
	s_andn2_b64 exec, exec, s[4:5]
	s_cbranch_execnz .LBB0_469
	s_or_b64 exec, exec, s[4:5]

.LBB0_501:
	v_mov_b32_e32 v12, v195
	v_readlane_b32 s24, v253, 5
	s_cmpk_gt_i32 s24, 0x9ff
	s_cbranch_scc1 .LBB0_659
	s_waitcnt vmcnt(1)
	v_lshrrev_b32_e32 v0, 1, v12
	v_and_b32_e32 v14, 24, v0
	v_lshlrev_b32_e32 v0, 1, v12
	v_and_b32_e32 v0, 24, v0
	v_and_or_b32 v31, v12, 3, v0
	v_add_u32_e32 v0, 64, v242
	v_cmp_lt_i32_e32 vcc, v237, v0
	s_movk_i32 s0, 0x1d1
	v_and_b32_e32 v17, 15, v12
	v_cndmask_b32_e32 v1, v220, v237, vcc
	v_cmp_lt_i32_e32 vcc, v236, v0
	v_cmp_gt_i32_e64 s[2:3], s0, v12
	v_lshlrev_b32_e32 v16, 1, v14
	v_cndmask_b32_e32 v0, v220, v236, vcc
	v_lshlrev_b32_e32 v77, 2, v0
	v_max_i32_e32 v0, 0xffffffd1, v12
	v_sub_u32_e32 v0, v0, v12
	v_add_u32_e32 v0, 0x1ff, v0
	v_lshlrev_b32_e32 v76, 2, v1
	s_movk_i32 s0, 0x3d0
	v_lshrrev_b32_e32 v1, 9, v0
	v_mad_u32_u24 v78, v17, s0, v16
	v_add_u32_e32 v1, 1, v1
	s_movk_i32 s0, 0x2200
	s_mul_i32 s26, s36, 0x744
	v_cmp_gt_u32_e32 vcc, s0, v0
	v_and_b32_e32 v81, 0xfffffe, v1
	v_lshlrev_b32_e32 v83, 2, v12
	v_ashrrev_i32_e32 v15, 6, v12
	s_lshl_b32 s25, s36, 2
	v_and_b32_e32 v79, 0xfffffe00, v0
	v_add_u32_e32 v80, s26, v12
	v_lshl_add_u32 v82, v81, 9, v12
	v_add_u32_e32 v13, 0x200, v12
	v_cmp_ne_u32_e64 s[4:5], v1, v81
	v_add_u32_e32 v84, 0x1fb00, v83
	v_lshlrev_b32_e32 v85, 3, v12
	s_mov_b32 s27, 0
	s_xor_b64 s[20:21], vcc, -1
	s_mov_b32 s28, s24
	s_mov_b32 s29, s24
	s_mov_b32 s99, 0
	s_branch .LBB0_504
.LBB0_503:
	s_or_b64 exec, exec, s[6:7]
	s_mov_b32 s0, 0xff61b1e6
	v_max3_f32 v0, v26, s0, v24
	v_max3_f32 v0, v0, v28, v25
	v_max3_f32 v0, v0, v34, v23
	v_max3_f32 v0, v0, v29, v27
	v_max3_f32 v0, v0, v32, v30
	v_max3_f32 v0, v0, v36, v35
	v_max3_f32 v0, v0, v38, v37
	v_max3_f32 v0, v0, v40, v39
	v_max3_f32 v0, v0, v42, v41
	v_max3_f32 v0, v0, v48, v43
	v_max3_f32 v0, v0, v51, v50
	v_max3_f32 v0, v0, v55, v54
	v_max3_f32 v0, v0, v61, v60
	v_max3_f32 v0, v0, v63, v62
	v_max3_f32 v0, v0, v88, v87
	v_max3_f32 v0, v0, v90, v89
	v_max3_f32 v0, v0, v92, v91
	v_max3_f32 v0, v0, v94, v93
	v_max3_f32 v0, v0, v96, v95
	v_max3_f32 v0, v0, v98, v97
	v_max3_f32 v0, v0, v100, v99
	v_max3_f32 v0, v0, v102, v101
	v_max3_f32 v0, v0, v104, v103
	v_max3_f32 v0, v0, v106, v105
	v_max3_f32 v0, v0, v108, v107
	v_max3_f32 v0, v0, v110, v109
	v_max3_f32 v0, v0, v112, v111
	v_max3_f32 v0, v0, v114, v113
	v_max3_f32 v0, v0, v116, v115
	v_max3_f32 v0, v0, v8, v9
	v_max3_f32 v0, v0, v22, v117
	v_max3_f32 v0, v0, v119, v118
	ds_bpermute_b32 v1, v76, v0
	s_mov_b32 s0, 0xa000000
	s_mov_b64 s[6:7], 0xa000400
	s_add_i32 s27, s27, 1
	s_waitcnt lgkmcnt(0)
	v_max_f32_e32 v1, v1, v1
	v_max_f32_e32 v0, v0, v1
	ds_bpermute_b32 v1, v77, v0
	s_waitcnt lgkmcnt(0)
	v_max_f32_e32 v1, v1, v1
	v_max_f32_e32 v120, v0, v1
	v_sub_f32_e32 v1, v24, v120
	v_mul_f32_e32 v1, 0x3fb8aa3b, v1
	v_exp_f32_e32 v47, v1
	v_sub_f32_e32 v1, v28, v120
	v_mul_f32_e32 v1, 0x3fb8aa3b, v1
	v_exp_f32_e32 v56, v1
	v_sub_f32_e32 v1, v25, v120
	v_mul_f32_e32 v1, 0x3fb8aa3b, v1
	v_exp_f32_e32 v57, v1
	v_sub_f32_e32 v1, v34, v120
	v_mul_f32_e32 v1, 0x3fb8aa3b, v1
	v_exp_f32_e32 v66, v1
	v_sub_f32_e32 v1, v23, v120
	v_mul_f32_e32 v1, 0x3fb8aa3b, v1
	v_exp_f32_e32 v67, v1
	v_sub_f32_e32 v1, v29, v120
	v_mul_f32_e32 v1, 0x3fb8aa3b, v1
	v_exp_f32_e32 v70, v1
	v_sub_f32_e32 v1, v27, v120
	v_mul_f32_e32 v1, 0x3fb8aa3b, v1
	v_exp_f32_e32 v71, v1
	v_sub_f32_e32 v1, v32, v120
	v_mul_f32_e32 v1, 0x3fb8aa3b, v1
	v_exp_f32_e32 v64, v1
	v_sub_f32_e32 v1, v30, v120
	v_mul_f32_e32 v1, 0x3fb8aa3b, v1
	v_exp_f32_e32 v65, v1
	v_sub_f32_e32 v1, v36, v120
	v_mul_f32_e32 v1, 0x3fb8aa3b, v1
	v_exp_f32_e32 v68, v1
	v_sub_f32_e32 v1, v35, v120
	v_mul_f32_e32 v1, 0x3fb8aa3b, v1
	v_exp_f32_e32 v69, v1
	v_sub_f32_e32 v1, v38, v120
	v_mul_f32_e32 v1, 0x3fb8aa3b, v1
	v_exp_f32_e32 v72, v1
	v_sub_f32_e32 v1, v37, v120
	v_mul_f32_e32 v1, 0x3fb8aa3b, v1
	v_exp_f32_e32 v73, v1
	v_sub_f32_e32 v1, v40, v120
	v_mul_f32_e32 v1, 0x3fb8aa3b, v1
	v_exp_f32_e32 v74, v1
	v_sub_f32_e32 v1, v39, v120
	v_mul_f32_e32 v1, 0x3fb8aa3b, v1
	v_exp_f32_e32 v75, v1
	v_sub_f32_e32 v1, v42, v120
	v_mul_f32_e32 v1, 0x3fb8aa3b, v1
	v_exp_f32_e32 v44, v1
	v_sub_f32_e32 v1, v41, v120
	v_mul_f32_e32 v1, 0x3fb8aa3b, v1
	v_exp_f32_e32 v45, v1
	v_sub_f32_e32 v1, v48, v120
	v_mul_f32_e32 v1, 0x3fb8aa3b, v1
	v_exp_f32_e32 v48, v1
	v_sub_f32_e32 v1, v43, v120
	v_mul_f32_e32 v1, 0x3fb8aa3b, v1
	v_exp_f32_e32 v49, v1
	v_sub_f32_e32 v1, v51, v120
	v_mul_f32_e32 v1, 0x3fb8aa3b, v1
	v_exp_f32_e32 v52, v1
	v_sub_f32_e32 v1, v50, v120
	v_mul_f32_e32 v1, 0x3fb8aa3b, v1
	v_exp_f32_e32 v53, v1
	v_sub_f32_e32 v1, v55, v120
	v_mul_f32_e32 v1, 0x3fb8aa3b, v1
	v_exp_f32_e32 v58, v1
	v_sub_f32_e32 v1, v54, v120
	v_sub_f32_e32 v0, v26, v120
	v_mul_f32_e32 v1, 0x3fb8aa3b, v1
	v_mul_f32_e32 v0, 0x3fb8aa3b, v0
	v_exp_f32_e32 v59, v1
	v_sub_f32_e32 v1, v61, v120
	v_exp_f32_e32 v46, v0
	v_mul_f32_e32 v1, 0x3fb8aa3b, v1
	v_exp_f32_e32 v50, v1
	v_sub_f32_e32 v1, v60, v120
	v_mul_f32_e32 v1, 0x3fb8aa3b, v1
	v_exp_f32_e32 v51, v1
	v_sub_f32_e32 v1, v63, v120
	v_add_f32_e32 v0, 0, v46
	v_mul_f32_e32 v1, 0x3fb8aa3b, v1
	v_add_f32_e32 v0, v47, v0
	v_exp_f32_e32 v54, v1
	v_sub_f32_e32 v1, v62, v120
	v_add_f32_e32 v0, v56, v0
	v_mul_f32_e32 v1, 0x3fb8aa3b, v1
	v_add_f32_e32 v0, v57, v0
	v_exp_f32_e32 v55, v1
	v_sub_f32_e32 v1, v88, v120
	v_add_f32_e32 v0, v66, v0
	v_mul_f32_e32 v1, 0x3fb8aa3b, v1
	v_add_f32_e32 v0, v67, v0
	v_exp_f32_e32 v60, v1
	v_sub_f32_e32 v1, v87, v120
	v_add_f32_e32 v0, v70, v0
	v_mul_f32_e32 v1, 0x3fb8aa3b, v1
	v_add_f32_e32 v0, v71, v0
	v_exp_f32_e32 v61, v1
	v_sub_f32_e32 v1, v90, v120
	v_add_f32_e32 v0, v64, v0
	v_mul_f32_e32 v1, 0x3fb8aa3b, v1
	v_add_f32_e32 v0, v65, v0
	v_exp_f32_e32 v62, v1
	v_sub_f32_e32 v1, v89, v120
	v_add_f32_e32 v0, v68, v0
	v_mul_f32_e32 v1, 0x3fb8aa3b, v1
	v_add_f32_e32 v0, v69, v0
	v_exp_f32_e32 v63, v1
	v_sub_f32_e32 v1, v92, v120
	v_add_f32_e32 v0, v72, v0
	v_mul_f32_e32 v1, 0x3fb8aa3b, v1
	v_add_f32_e32 v0, v73, v0
	v_exp_f32_e32 v26, v1
	v_sub_f32_e32 v1, v91, v120
	v_add_f32_e32 v0, v74, v0
	v_mul_f32_e32 v1, 0x3fb8aa3b, v1
	v_add_f32_e32 v0, v75, v0
	v_exp_f32_e32 v27, v1
	v_sub_f32_e32 v1, v94, v120
	v_add_f32_e32 v0, v44, v0
	v_mul_f32_e32 v1, 0x3fb8aa3b, v1
	v_add_f32_e32 v0, v45, v0
	v_exp_f32_e32 v28, v1
	v_sub_f32_e32 v1, v93, v120
	v_add_f32_e32 v0, v48, v0
	v_mul_f32_e32 v1, 0x3fb8aa3b, v1
	v_add_f32_e32 v0, v49, v0
	v_exp_f32_e32 v29, v1
	v_sub_f32_e32 v1, v96, v120
	v_add_f32_e32 v0, v52, v0
	v_mul_f32_e32 v1, 0x3fb8aa3b, v1
	v_add_f32_e32 v0, v53, v0
	v_exp_f32_e32 v34, v1
	v_sub_f32_e32 v1, v95, v120
	v_add_f32_e32 v0, v58, v0
	v_mul_f32_e32 v1, 0x3fb8aa3b, v1
	v_add_f32_e32 v0, v59, v0
	v_exp_f32_e32 v35, v1
	v_sub_f32_e32 v1, v98, v120
	v_add_f32_e32 v0, v50, v0
	v_mul_f32_e32 v1, 0x3fb8aa3b, v1
	v_add_f32_e32 v0, v51, v0
	v_exp_f32_e32 v38, v1
	v_sub_f32_e32 v1, v97, v120
	v_add_f32_e32 v0, v54, v0
	v_mul_f32_e32 v1, 0x3fb8aa3b, v1
	v_add_f32_e32 v0, v55, v0
	v_exp_f32_e32 v39, v1
	v_sub_f32_e32 v1, v100, v120
	v_add_f32_e32 v0, v60, v0
	v_mul_f32_e32 v1, 0x3fb8aa3b, v1
	v_add_f32_e32 v0, v61, v0
	v_exp_f32_e32 v32, v1
	v_sub_f32_e32 v1, v99, v120
	v_add_f32_e32 v0, v62, v0
	v_mul_f32_e32 v1, 0x3fb8aa3b, v1
	v_add_f32_e32 v0, v63, v0
	v_exp_f32_e32 v33, v1
	v_sub_f32_e32 v1, v102, v120
	v_add_f32_e32 v0, v26, v0
	v_mul_f32_e32 v1, 0x3fb8aa3b, v1
	v_add_f32_e32 v0, v27, v0
	v_exp_f32_e32 v36, v1
	v_sub_f32_e32 v1, v101, v120
	v_add_f32_e32 v0, v28, v0
	v_mul_f32_e32 v1, 0x3fb8aa3b, v1
	v_add_f32_e32 v0, v29, v0
	v_exp_f32_e32 v37, v1
	v_sub_f32_e32 v1, v104, v120
	v_add_f32_e32 v0, v34, v0
	v_mul_f32_e32 v1, 0x3fb8aa3b, v1
	v_add_f32_e32 v0, v35, v0
	v_exp_f32_e32 v40, v1
	v_sub_f32_e32 v1, v103, v120
	v_add_f32_e32 v0, v38, v0
	v_mul_f32_e32 v1, 0x3fb8aa3b, v1
	v_add_f32_e32 v0, v39, v0
	v_exp_f32_e32 v41, v1
	v_sub_f32_e32 v1, v106, v120
	v_add_f32_e32 v0, v32, v0
	v_mul_f32_e32 v1, 0x3fb8aa3b, v1
	v_add_f32_e32 v0, v33, v0
	v_exp_f32_e32 v42, v1
	v_sub_f32_e32 v1, v105, v120
	v_add_f32_e32 v0, v36, v0
	v_mul_f32_e32 v1, 0x3fb8aa3b, v1
	v_add_f32_e32 v0, v37, v0
	v_exp_f32_e32 v43, v1
	v_add_f32_e32 v0, v40, v0
	v_add_f32_e32 v0, v41, v0
	v_add_f32_e32 v0, v42, v0
	v_add_f32_e32 v1, v43, v0
	v_sub_f32_e32 v0, v108, v120
	v_mul_f32_e32 v0, 0x3fb8aa3b, v0
	v_exp_f32_e32 v0, v0
	v_sub_f32_e32 v5, v112, v120
	v_mul_f32_e32 v5, 0x3fb8aa3b, v5
	v_exp_f32_e32 v6, v5
	v_add_f32_e32 v2, v0, v1
	v_sub_f32_e32 v1, v107, v120
	v_mul_f32_e32 v1, 0x3fb8aa3b, v1
	v_exp_f32_e32 v1, v1
	v_sub_f32_e32 v5, v111, v120
	v_mul_f32_e32 v5, 0x3fb8aa3b, v5
	v_exp_f32_e32 v7, v5
	v_add_f32_e32 v3, v1, v2
	v_sub_f32_e32 v2, v110, v120
	v_mul_f32_e32 v2, 0x3fb8aa3b, v2
	v_exp_f32_e32 v2, v2
	v_sub_f32_e32 v5, v114, v120
	v_mul_f32_e32 v5, 0x3fb8aa3b, v5
	v_exp_f32_e32 v10, v5
	v_add_f32_e32 v4, v2, v3
	v_sub_f32_e32 v3, v109, v120
	v_mul_f32_e32 v3, 0x3fb8aa3b, v3
	v_exp_f32_e32 v3, v3
	v_sub_f32_e32 v5, v113, v120
	v_mul_f32_e32 v5, 0x3fb8aa3b, v5
	v_exp_f32_e32 v11, v5
	v_add_f32_e32 v4, v3, v4
	v_add_f32_e32 v4, v6, v4
	v_add_f32_e32 v4, v7, v4
	v_add_f32_e32 v4, v10, v4
	v_add_f32_e32 v5, v11, v4
	v_sub_f32_e32 v4, v116, v120
	v_mul_f32_e32 v4, 0x3fb8aa3b, v4
	v_exp_f32_e32 v4, v4
	v_sub_f32_e32 v8, v8, v120
	v_mul_f32_e32 v8, 0x3fb8aa3b, v8
	v_sub_f32_e32 v9, v9, v120
	v_add_f32_e32 v23, v4, v5
	v_sub_f32_e32 v5, v115, v120
	v_mul_f32_e32 v5, 0x3fb8aa3b, v5
	v_exp_f32_e32 v5, v5
	v_exp_f32_e32 v8, v8
	v_mul_f32_e32 v9, 0x3fb8aa3b, v9
	v_sub_f32_e32 v22, v22, v120
	v_exp_f32_e32 v9, v9
	v_mul_f32_e32 v22, 0x3fb8aa3b, v22
	v_exp_f32_e32 v22, v22
	v_add_f32_e32 v23, v5, v23
	v_add_f32_e32 v23, v8, v23
	v_add_f32_e32 v23, v9, v23
	v_add_f32_e32 v24, v22, v23
	v_sub_f32_e32 v23, v117, v120
	v_mul_f32_e32 v23, 0x3fb8aa3b, v23
	v_exp_f32_e32 v23, v23
	s_nop 0
	v_add_f32_e32 v25, v23, v24
	v_sub_f32_e32 v24, v119, v120
	v_mul_f32_e32 v24, 0x3fb8aa3b, v24
	v_exp_f32_e32 v24, v24
	s_nop 0
	v_add_f32_e32 v30, v24, v25
	v_sub_f32_e32 v25, v118, v120
	v_mul_f32_e32 v25, 0x3fb8aa3b, v25
	v_exp_f32_e32 v25, v25
	s_nop 0
	v_add_f32_e32 v30, v25, v30
	ds_bpermute_b32 v87, v76, v30
	s_waitcnt lgkmcnt(0)
	v_add_f32_e32 v30, v30, v87
	ds_bpermute_b32 v87, v77, v30
	s_waitcnt lgkmcnt(0)
	v_add_f32_e32 v30, v30, v87
	v_rcp_f32_e32 v30, v30
	v_lshl_add_u32 v87, v86, 1, v78
	ds_read_b128 v[92:95], v87 offset:65280
	v_add_u32_e32 v86, 0xff00, v87
	v_pk_mul_f32 v[56:57], v[56:57], v[30:31] op_sel_hi:[1,0]
	v_pk_mul_f32 v[46:47], v[46:47], v[30:31] op_sel_hi:[1,0]
	v_cvt_pk_bf16_f32 v89, v56, v57
	v_pk_mul_f32 v[56:57], v[70:71], v[30:31] op_sel_hi:[1,0]
	ds_read_b128 v[96:99], v86 offset:15616
	v_cvt_pk_bf16_f32 v91, v56, v57
	v_pk_mul_f32 v[56:57], v[68:69], v[30:31] op_sel_hi:[1,0]
	ds_read_b128 v[68:71], v87 offset:65344
	v_cvt_pk_bf16_f32 v88, v46, v47
	v_pk_mul_f32 v[46:47], v[66:67], v[30:31] op_sel_hi:[1,0]
	ds_read_b128 v[100:103], v86 offset:31232
	v_cvt_pk_bf16_f32 v90, v46, v47
	v_pk_mul_f32 v[46:47], v[64:65], v[30:31] op_sel_hi:[1,0]
	v_cvt_pk_bf16_f32 v65, v56, v57
	v_cvt_pk_bf16_f32 v64, v46, v47
	v_pk_mul_f32 v[46:47], v[72:73], v[30:31] op_sel_hi:[1,0]
	v_pk_mul_f32 v[56:57], v[74:75], v[30:31] op_sel_hi:[1,0]
	v_cvt_pk_bf16_f32 v66, v46, v47
	v_cvt_pk_bf16_f32 v67, v56, v57
	ds_read_b128 v[72:75], v86 offset:15680
	v_pk_mul_f32 v[46:47], v[48:49], v[30:31] op_sel_hi:[1,0]
	v_pk_mul_f32 v[48:49], v[58:59], v[30:31] op_sel_hi:[1,0]
	ds_read_b128 v[56:59], v87 offset:65408
	s_waitcnt lgkmcnt(5)
	v_mfma_f32_16x16x32_bf16 v[92:95], v[92:95], v[88:91], 0
	ds_read_b128 v[104:107], v86 offset:46848
	v_pk_mul_f32 v[44:45], v[44:45], v[30:31] op_sel_hi:[1,0]
	v_pk_mul_f32 v[26:27], v[26:27], v[30:31] op_sel_hi:[1,0]
	s_waitcnt lgkmcnt(5)
	v_mfma_f32_16x16x32_bf16 v[96:99], v[96:99], v[88:91], 0
	v_cvt_pk_bf16_f32 v44, v44, v45
	v_cvt_pk_bf16_f32 v45, v46, v47
	v_pk_mul_f32 v[46:47], v[52:53], v[30:31] op_sel_hi:[1,0]
	s_waitcnt lgkmcnt(4)
	v_mfma_f32_16x16x32_bf16 v[68:71], v[68:71], v[64:67], v[92:95]
	v_cvt_pk_bf16_f32 v46, v46, v47
	v_cvt_pk_bf16_f32 v47, v48, v49
	v_pk_mul_f32 v[48:49], v[50:51], v[30:31] op_sel_hi:[1,0]
	v_pk_mul_f32 v[50:51], v[54:55], v[30:31] op_sel_hi:[1,0]
	v_cvt_pk_bf16_f32 v48, v48, v49
	v_cvt_pk_bf16_f32 v49, v50, v51
	v_pk_mul_f32 v[50:51], v[60:61], v[30:31] op_sel_hi:[1,0]
	v_pk_mul_f32 v[52:53], v[62:63], v[30:31] op_sel_hi:[1,0]
	s_waitcnt lgkmcnt(2)
	v_mfma_f32_16x16x32_bf16 v[72:75], v[72:75], v[64:67], v[96:99]
	ds_read_b128 v[92:95], v86 offset:31296
	v_cvt_pk_bf16_f32 v50, v50, v51
	v_cvt_pk_bf16_f32 v51, v52, v53
	ds_read_b128 v[96:99], v86 offset:46912
	ds_read_b128 v[52:55], v87 offset:65472
	s_waitcnt lgkmcnt(4)
	v_mfma_f32_16x16x32_bf16 v[56:59], v[56:59], v[44:47], v[68:71]
	v_mul_f32_e64 v28, v28, v30
	v_mul_f32_e64 v29, v29, v30
	v_cvt_pk_bf16_f32 v26, v26, v27
	v_cvt_pk_bf16_f32 v27, v28, v29
	ds_read_b128 v[68:71], v86 offset:15744
	v_mfma_f32_16x16x32_bf16 v[100:103], v[100:103], v[88:91], 0
	v_mul_f32_e64 v28, v34, v30
	v_mul_f32_e64 v29, v35, v30
	v_pk_mul_f32 v[34:35], v[38:39], v[30:31] op_sel_hi:[1,0]
	v_cvt_pk_bf16_f32 v28, v28, v29
	s_waitcnt lgkmcnt(4)
	v_mfma_f32_16x16x32_bf16 v[88:91], v[104:107], v[88:91], 0
	v_cvt_pk_bf16_f32 v29, v34, v35
	v_pk_mul_f32 v[32:33], v[32:33], v[30:31] op_sel_hi:[1,0]
	v_pk_mul_f32 v[34:35], v[36:37], v[30:31] op_sel_hi:[1,0]
	s_waitcnt lgkmcnt(3)
	v_mfma_f32_16x16x32_bf16 v[92:95], v[92:95], v[64:67], v[100:103]
	v_cvt_pk_bf16_f32 v32, v32, v33
	v_cvt_pk_bf16_f32 v33, v34, v35
	v_pk_mul_f32 v[34:35], v[40:41], v[30:31] op_sel_hi:[1,0]
	s_waitcnt lgkmcnt(2)
	v_mfma_f32_16x16x32_bf16 v[64:67], v[96:99], v[64:67], v[88:91]
	v_mul_f32_e64 v36, v42, v30
	v_mul_f32_e64 v37, v43, v30
	ds_read_b128 v[60:63], v86 offset:31424
	v_cvt_pk_bf16_f32 v34, v34, v35
	ds_read_b128 v[88:91], v86 offset:46976
	s_waitcnt lgkmcnt(3)
	v_mfma_f32_16x16x32_bf16 v[52:55], v[52:55], v[48:51], v[56:59]
	v_cvt_pk_bf16_f32 v35, v36, v37
	ds_read_b128 v[36:39], v86 offset:320
	v_pk_mul_f32 v[0:1], v[0:1], v[30:31] op_sel_hi:[1,0]
	ds_read_b128 v[56:59], v86 offset:15808
	s_waitcnt lgkmcnt(4)
	v_mfma_f32_16x16x32_bf16 v[68:71], v[68:71], v[44:47], v[72:75]
	v_mul_f32_e64 v2, v2, v30
	v_mul_f32_e64 v3, v3, v30
	v_cvt_pk_bf16_f32 v0, v0, v1
	v_cvt_pk_bf16_f32 v1, v2, v3
	ds_read_b128 v[72:75], v86 offset:31360
	s_waitcnt lgkmcnt(0)
	v_mfma_f32_16x16x32_bf16 v[72:75], v[72:75], v[44:47], v[92:95]
	v_mul_f32_e64 v2, v6, v30
	v_mul_f32_e64 v3, v7, v30
	v_pk_mul_f32 v[6:7], v[10:11], v[30:31] op_sel_hi:[1,0]
	v_cvt_pk_bf16_f32 v2, v2, v3
	v_mfma_f32_16x16x32_bf16 v[44:47], v[88:91], v[44:47], v[64:67]
	v_cvt_pk_bf16_f32 v3, v6, v7
	v_pk_mul_f32 v[4:5], v[4:5], v[30:31] op_sel_hi:[1,0]
	v_pk_mul_f32 v[6:7], v[8:9], v[30:31] op_sel_hi:[1,0]
	ds_read_b128 v[64:67], v86 offset:47040
	v_cvt_pk_bf16_f32 v4, v4, v5
	v_cvt_pk_bf16_f32 v5, v6, v7
	v_pk_mul_f32 v[6:7], v[22:23], v[30:31] op_sel_hi:[1,0]
	v_pk_mul_f32 v[8:9], v[24:25], v[30:31] op_sel_hi:[1,0]
	v_mfma_f32_16x16x32_bf16 v[56:59], v[56:59], v[48:51], v[68:71]
	v_cvt_pk_bf16_f32 v6, v6, v7
	v_cvt_pk_bf16_f32 v7, v8, v9
	ds_read_b128 v[8:11], v86 offset:448
	v_mfma_f32_16x16x32_bf16 v[60:63], v[60:63], v[48:51], v[72:75]
	ds_read_b128 v[40:43], v86 offset:15936
	ds_read_b128 v[22:25], v86 offset:16064
	s_waitcnt lgkmcnt(3)
	v_mfma_f32_16x16x32_bf16 v[44:47], v[64:67], v[48:51], v[44:47]
	ds_read_b128 v[48:51], v86 offset:256
	s_waitcnt lgkmcnt(0)
	v_mfma_f32_16x16x32_bf16 v[48:51], v[48:51], v[26:29], v[52:55]
	s_nop 2
	ds_read_b128 v[52:55], v86 offset:15872
	s_waitcnt lgkmcnt(0)
	v_mfma_f32_16x16x32_bf16 v[52:55], v[52:55], v[26:29], v[56:59]
	s_nop 2
	ds_read_b128 v[56:59], v86 offset:31488
	s_waitcnt lgkmcnt(0)
	v_mfma_f32_16x16x32_bf16 v[56:59], v[56:59], v[26:29], v[60:63]
	s_nop 2
	ds_read_b128 v[60:63], v86 offset:47104
	v_mfma_f32_16x16x32_bf16 v[36:39], v[36:39], v[32:35], v[48:51]
	s_nop 2
	ds_read_b128 v[48:51], v86 offset:47168
	s_waitcnt lgkmcnt(1)
	v_mfma_f32_16x16x32_bf16 v[26:29], v[60:63], v[26:29], v[44:47]
	s_nop 2
	ds_read_b128 v[44:47], v86 offset:31552
	v_mfma_f32_16x16x32_bf16 v[40:43], v[40:43], v[32:35], v[52:55]
	s_waitcnt lgkmcnt(0)
	v_mfma_f32_16x16x32_bf16 v[44:47], v[44:47], v[32:35], v[56:59]
	v_mfma_f32_16x16x32_bf16 v[26:29], v[48:51], v[32:35], v[26:29]
	ds_read_b128 v[32:35], v86 offset:384
	s_waitcnt lgkmcnt(0)
	v_mfma_f32_16x16x32_bf16 v[32:35], v[32:35], v[0:3], v[36:39]
	s_nop 2
	ds_read_b128 v[36:39], v86 offset:16000
	s_waitcnt lgkmcnt(0)
	v_mfma_f32_16x16x32_bf16 v[36:39], v[36:39], v[0:3], v[40:43]
	s_nop 2
	ds_read_b128 v[40:43], v86 offset:31616
	s_waitcnt lgkmcnt(0)
	v_mfma_f32_16x16x32_bf16 v[40:43], v[40:43], v[0:3], v[44:47]
	s_nop 2
	ds_read_b128 v[44:47], v86 offset:47232
	v_mfma_f32_16x16x32_bf16 v[8:11], v[8:11], v[4:7], v[32:35]
	s_nop 2
	ds_read_b128 v[32:35], v86 offset:47296
	s_waitcnt lgkmcnt(1)
	v_mfma_f32_16x16x32_bf16 v[0:3], v[44:47], v[0:3], v[26:29]
	s_nop 2
	ds_read_b128 v[26:29], v86 offset:31680
	v_mfma_f32_16x16x32_bf16 v[22:25], v[22:25], v[4:7], v[36:39]
	s_waitcnt lgkmcnt(0)
	v_mfma_f32_16x16x32_bf16 v[26:29], v[26:29], v[4:7], v[40:43]
	v_mfma_f32_16x16x32_bf16 v[0:3], v[32:35], v[4:7], v[0:3]
	v_lshlrev_b64 v[4:5], 11, v[20:21]
	v_lshl_add_u64 v[4:5], s[86:87], 0, v[4:5]
	v_lshl_add_u64 v[4:5], v[18:19], 1, v[4:5]
	v_lshl_add_u64 v[18:19], v[4:5], 0, v[192:193]
	v_cvt_pk_bf16_f32 v4, v8, v9
	v_add_co_u32_e32 v8, vcc, s0, v18
	v_readlane_b32 s0, v253, 0
	v_cvt_pk_bf16_f32 v5, v10, v11
	v_cvt_pk_bf16_f32 v6, v22, v23
	v_cvt_pk_bf16_f32 v7, v24, v25
	v_addc_co_u32_e32 v9, vcc, 0, v19, vcc
	s_add_i32 s29, s29, s0
	s_add_i32 s28, s28, s0
	v_lshl_add_u64 v[20:21], v[18:19], 0, s[6:7]
	global_store_dwordx4 v[8:9], v[4:7], off offset:1024
	s_cmpk_lt_i32 s29, 0xa00
	s_nop 0
	v_cvt_pk_bf16_f32 v4, v26, v27
	v_cvt_pk_bf16_f32 v5, v28, v29
	v_cvt_pk_bf16_f32 v6, v0, v1
	v_cvt_pk_bf16_f32 v7, v2, v3
	global_store_dwordx4 v[20:21], v[4:7], off offset:64
	s_barrier
	s_cbranch_scc0 .LBB0_659
	s_branch .Lna_top

.LBB0_513:
	s_and_b32 s9, s29, 3
	s_and_b32 s0, s7, s0
	s_lshl_b32 s17, s0, 3
	s_add_i32 s7, s17, -4
	s_min_i32 s7, s7, s18
	s_cmp_lg_u32 s0, 0
	s_cselect_b32 s16, s7, 0
	s_or_b32 s0, s17, 3
	s_min_u32 s0, s0, s18
	s_sub_i32 s7, s0, s16
	s_add_i32 s7, s7, 8
	s_movk_i32 s79, 0x88
	v_readfirstlane_b32 s10, v195
	s_nop 0
	s_lshr_b32 s11, s10, 8
	s_lshr_b32 s10, s10, 6
	s_sub_i32 s0, s7, s11
	s_branch .Lna_L
.Lna_top:
	v_readlane_b32 s0, v80, 0
	v_readlane_b32 s7, v80, 1
	v_readlane_b32 s6, v80, 2
	v_readlane_b32 s8, v80, 3
	v_readlane_b32 s9, v80, 4
	v_readlane_b32 s16, v80, 5
	v_readlane_b32 s17, v80, 6
	v_readlane_b32 s18, v80, 7
	v_readlane_b32 s19, v80, 8
	s_movk_i32 s79, 0x88
	v_readfirstlane_b32 s10, v195
	s_nop 1
	s_lshr_b32 s11, s10, 8
	s_lshr_b32 s10, s10, 6

.Lna_vwr_done:
	v_mov_b32_e32 v148, v248
	v_mov_b32_e32 v149, v249
	v_mov_b32_e32 v150, v250
	v_mov_b32_e32 v151, v251
	v_mov_b32_e32 v152, v144
	v_mov_b32_e32 v153, v145
	v_mov_b32_e32 v154, v146
	v_mov_b32_e32 v155, v147
	s_waitcnt lgkmcnt(0)
	s_barrier
	v_mov_b32_e32 v79, v80
	v_readlane_b32 s100, v253, 0
	s_nop 3
	s_add_i32 s101, s29, s100
	s_cmpk_lt_i32 s101, 0xa00
	s_cbranch_scc0 .Lna_C
	s_mov_b32 s29, s101
	s_mov_b32 s99, 1
	s_branch .LBB0_504

.Lna_vld_done:
	v_add_u32_e32 v0, s17, v15
	v_lshlrev_b32_e32 v0, 6, v0
	v_lshl_or_b32 v1, s19, 4, v17
	v_add3_u32 v0, s6, v1, v0
	v_ashrrev_i32_e32 v1, 31, v0
	v_lshlrev_b64 v[0:1], 9, v[0:1]
	v_readlane_b32 s12, v254, 0
	v_readlane_b32 s13, v254, 1
	s_lshl_b32 s14, s9, 7
	s_mov_b32 s15, 0
	v_lshlrev_b32_e32 v2, 1, v14
	v_mov_b32_e32 v3, 0
	s_nop 0
	v_lshl_add_u64 v[0:1], s[12:13], 0, v[0:1]
	v_lshl_add_u64 v[0:1], v[0:1], 0, s[14:15]
	v_lshl_add_u64 v[0:1], v[0:1], 0, v[2:3]
	global_load_dwordx4 v[248:251], v[0:1], off
	global_load_dwordx4 v[144:147], v[0:1], off offset:64
	v_writelane_b32 v80, s0, 0
	v_writelane_b32 v80, s7, 1
	v_writelane_b32 v80, s6, 2
	v_writelane_b32 v80, s8, 3
	v_writelane_b32 v80, s9, 4
	v_writelane_b32 v80, s16, 5
	v_writelane_b32 v80, s17, 6
	v_writelane_b32 v80, s18, 7
	v_writelane_b32 v80, s19, 8
	s_cmp_eq_u32 s99, 0
	s_cbranch_scc1 .Lna_top
	s_sub_i32 s29, s29, s100
	v_readlane_b32 s6, v79, 2
	v_readlane_b32 s8, v79, 3
	v_readlane_b32 s9, v79, 4
	v_readlane_b32 s16, v79, 5
	v_readlane_b32 s17, v79, 6
	v_readlane_b32 s18, v79, 7
	v_readlane_b32 s19, v79, 8
	s_nop 1
	s_branch .Lna_C
